# attention loops: O-accumulator rescale v_pk_mul_f32 split into scalar v_mul_f32 pairs (packed fp32 ops that feed the following MFMAs' accumulators), bit-identical
# speedup vs baseline: 1.0068x; 1.0048x over previous
.LBB0_459:
	ds_read_b64_tr_b16 v[188:189], v153 offset:9216
	ds_read_b64_tr_b16 v[190:191], v153 offset:9984
	ds_read_b64_tr_b16 v[192:193], v153 offset:9280
	ds_read_b64_tr_b16 v[194:195], v153 offset:10048
	ds_read_b64_tr_b16 v[196:197], v153 offset:12288
	ds_read_b64_tr_b16 v[198:199], v153 offset:13056
	ds_read_b64_tr_b16 v[200:201], v153 offset:12352
	ds_read_b64_tr_b16 v[202:203], v153 offset:13120
	ds_read_b64_tr_b16 v[204:205], v153 offset:15360
	ds_read_b64_tr_b16 v[206:207], v153 offset:16128
	ds_read_b64_tr_b16 v[208:209], v153 offset:15424
	ds_read_b64_tr_b16 v[210:211], v153 offset:16192
	ds_read_b64_tr_b16 v[212:213], v153 offset:18432
	ds_read_b64_tr_b16 v[214:215], v153 offset:19200
	ds_read_b64_tr_b16 v[216:217], v153 offset:18496
	ds_read_b64_tr_b16 v[218:219], v153 offset:19264
	s_nop 0
	v_max_f32_e32 v2, v147, v147
	s_nop 2
	v_max_f32_e32 v50, v146, v146
	v_max_f32_e32 v2, v50, v2
	v_max3_f32 v2, v2, v144, v145
	v_max3_f32 v2, v2, v142, v143
	v_max3_f32 v2, v2, v140, v141
	v_max3_f32 v2, v2, v138, v139
	v_max3_f32 v2, v2, v134, v135
	v_max3_f32 v2, v2, v130, v131
	v_max3_f32 v2, v2, v16, v17
	v_max3_f32 v2, v2, v136, v137
	v_max3_f32 v2, v2, v132, v133
	v_max3_f32 v2, v2, v14, v15
	v_max3_f32 v2, v2, v12, v13
	v_max3_f32 v2, v2, v10, v11
	v_max3_f32 v2, v2, v8, v9
	v_max3_f32 v2, v2, v6, v7
	v_max3_f32 v2, v2, v4, v5
	v_mov_b32_e32 v50, v2
	s_nop 1
	v_permlane32_swap_b32_e32 v50, v2
	v_max3_f32 v50, v173, v2, v50
	v_sub_f32_e32 v2, v173, v50
	v_exp_f32_e32 v2, v2
	s_nop 0
	v_cmp_neq_f32_e32 vcc, 1.0, v2
	s_cbranch_vccz .LBB0_461
	v_mul_f32_e32 v48, v2, v48
	v_mul_f32_e32 v49, v2, v49
	v_mul_f32_e32 v46, v2, v46
	v_mul_f32_e32 v47, v2, v47
	v_mul_f32_e32 v44, v2, v44
	v_mul_f32_e32 v45, v2, v45
	v_mul_f32_e32 v42, v2, v42
	v_mul_f32_e32 v43, v2, v43
	v_mul_f32_e32 v40, v2, v40
	v_mul_f32_e32 v41, v2, v41
	v_mul_f32_e32 v38, v2, v38
	v_mul_f32_e32 v39, v2, v39
	v_mul_f32_e32 v36, v2, v36
	v_mul_f32_e32 v37, v2, v37
	v_mul_f32_e32 v34, v2, v34
	v_mul_f32_e32 v35, v2, v35
	v_mul_f32_e32 v32, v2, v32
	v_mul_f32_e32 v33, v2, v33
	v_mul_f32_e32 v30, v2, v30
	v_mul_f32_e32 v31, v2, v31
	v_mul_f32_e32 v28, v2, v28
	v_mul_f32_e32 v29, v2, v29
	v_mul_f32_e32 v26, v2, v26
	v_mul_f32_e32 v27, v2, v27
	v_mul_f32_e32 v24, v2, v24
	v_mul_f32_e32 v25, v2, v25
	v_mul_f32_e32 v22, v2, v22
	v_mul_f32_e32 v23, v2, v23
	v_mul_f32_e32 v20, v2, v20
	v_mul_f32_e32 v21, v2, v21
	v_mul_f32_e32 v18, v2, v18
	v_mul_f32_e32 v19, v2, v19

.LBB0_1611:
	v_lshl_add_u64 v[66:67], v[214:215], 0, s[56:57]
	v_cndmask_b32_e64 v67, v217, v67, s[4:5]
	v_cndmask_b32_e64 v66, v216, v66, s[4:5]
	s_waitcnt vmcnt(63) expcnt(7) lgkmcnt(15)
	s_barrier
	s_waitcnt vmcnt(4)
	ds_write_b128 v229, v[146:149]
	s_waitcnt vmcnt(3)
	ds_write_b128 v230, v[150:153]
	s_waitcnt vmcnt(2)
	ds_write_b128 v231, v[154:157]
	s_waitcnt vmcnt(1)
	ds_write_b128 v232, v[162:165] offset:25600
	s_waitcnt vmcnt(0)
	ds_write_b128 v233, v[158:161] offset:25600
	s_waitcnt lgkmcnt(0)
	s_barrier
	global_load_dwordx4 v[146:149], v[66:67], off
	v_lshl_add_u64 v[66:67], v[210:211], 0, s[56:57]
	v_cndmask_b32_e64 v67, v213, v67, s[8:9]
	v_cndmask_b32_e64 v66, v212, v66, s[8:9]
	global_load_dwordx4 v[150:153], v[66:67], off
	v_lshl_add_u64 v[66:67], v[206:207], 0, s[56:57]
	v_cndmask_b32_e64 v67, v209, v67, s[12:13]
	v_cndmask_b32_e64 v66, v208, v66, s[12:13]
	global_load_dwordx4 v[154:157], v[66:67], off
	v_lshl_add_u64 v[66:67], v[204:205], 0, s[56:57]
	v_lshl_add_u64 v[68:69], v[202:203], 0, s[56:57]
	global_load_dwordx4 v[162:165], v[66:67], off
	global_load_dwordx4 v[158:161], v[68:69], off
	s_cmp_gt_i32 s58, s29
	s_cbranch_scc1 .LBB0_1615
	v_add_u32_e32 v235, v226, v225
	ds_read_b128 v[66:69], v235
	ds_read_b128 v[236:239], v235 offset:32
	ds_read_b128 v[70:73], v235 offset:12800
	ds_read_b128 v[244:247], v235 offset:12832
	s_waitcnt lgkmcnt(3)
	v_mfma_f32_32x32x16_bf16 v[82:97], v[66:69], v[142:145], 0
	ds_read_b128 v[248:251], v235 offset:64
	ds_read_b128 v[252:255], v235 offset:12864
	s_waitcnt lgkmcnt(3)
	v_mfma_f32_32x32x16_bf16 v[66:81], v[70:73], v[142:145], 0
	v_mfma_f32_32x32x16_bf16 v[82:97], v[236:239], v[138:141], v[82:97]
	s_waitcnt lgkmcnt(2)
	v_mfma_f32_32x32x16_bf16 v[66:81], v[244:247], v[138:141], v[66:81]
	ds_read_b128 v[236:239], v235 offset:96
	ds_read_b128 v[244:247], v235 offset:12896
	s_waitcnt lgkmcnt(3)
	v_mfma_f32_32x32x16_bf16 v[82:97], v[248:251], v[134:137], v[82:97]
	s_waitcnt lgkmcnt(2)
	v_mfma_f32_32x32x16_bf16 v[66:81], v[252:255], v[134:137], v[66:81]
	ds_read_b128 v[248:251], v235 offset:128
	ds_read_b128 v[252:255], v235 offset:12928
	s_waitcnt lgkmcnt(3)
	v_mfma_f32_32x32x16_bf16 v[82:97], v[236:239], v[130:133], v[82:97]
	s_waitcnt lgkmcnt(2)
	v_mfma_f32_32x32x16_bf16 v[66:81], v[244:247], v[130:133], v[66:81]
	ds_read_b128 v[236:239], v235 offset:160
	ds_read_b128 v[244:247], v235 offset:12960
	s_waitcnt lgkmcnt(3)
	v_mfma_f32_32x32x16_bf16 v[82:97], v[248:251], v[126:129], v[82:97]
	s_waitcnt lgkmcnt(2)
	v_mfma_f32_32x32x16_bf16 v[66:81], v[252:255], v[126:129], v[66:81]
	ds_read_b128 v[248:251], v235 offset:192
	ds_read_b128 v[252:255], v235 offset:12992
	s_waitcnt lgkmcnt(3)
	v_mfma_f32_32x32x16_bf16 v[82:97], v[236:239], v[122:125], v[82:97]
	s_waitcnt lgkmcnt(2)
	v_mfma_f32_32x32x16_bf16 v[66:81], v[244:247], v[122:125], v[66:81]
	ds_read_b128 v[236:239], v235 offset:224
	ds_read_b128 v[244:247], v235 offset:13024
	s_waitcnt lgkmcnt(3)
	v_mfma_f32_32x32x16_bf16 v[82:97], v[248:251], v[118:121], v[82:97]
	s_waitcnt lgkmcnt(2)
	v_mfma_f32_32x32x16_bf16 v[66:81], v[252:255], v[118:121], v[66:81]
	ds_read_b128 v[248:251], v235 offset:256
	ds_read_b128 v[252:255], v235 offset:13056
	s_waitcnt lgkmcnt(3)
	v_mfma_f32_32x32x16_bf16 v[82:97], v[236:239], v[114:117], v[82:97]
	s_waitcnt lgkmcnt(2)
	v_mfma_f32_32x32x16_bf16 v[66:81], v[244:247], v[114:117], v[66:81]
	ds_read_b128 v[236:239], v235 offset:288
	ds_read_b128 v[244:247], v235 offset:13088
	s_waitcnt lgkmcnt(3)
	v_mfma_f32_32x32x16_bf16 v[82:97], v[248:251], v[110:113], v[82:97]
	s_waitcnt lgkmcnt(2)
	v_mfma_f32_32x32x16_bf16 v[66:81], v[252:255], v[110:113], v[66:81]
	ds_read_b128 v[248:251], v235 offset:320
	ds_read_b128 v[252:255], v235 offset:13120
	s_waitcnt lgkmcnt(3)
	v_mfma_f32_32x32x16_bf16 v[82:97], v[236:239], v[106:109], v[82:97]
	s_waitcnt lgkmcnt(2)
	v_mfma_f32_32x32x16_bf16 v[66:81], v[244:247], v[106:109], v[66:81]
	ds_read_b128 v[236:239], v235 offset:352
	ds_read_b128 v[244:247], v235 offset:13152
	s_waitcnt lgkmcnt(3)
	v_mfma_f32_32x32x16_bf16 v[82:97], v[248:251], v[102:105], v[82:97]
	s_waitcnt lgkmcnt(2)
	v_mfma_f32_32x32x16_bf16 v[66:81], v[252:255], v[102:105], v[66:81]
	s_waitcnt lgkmcnt(1)
	v_mfma_f32_32x32x16_bf16 v[82:97], v[236:239], v[98:101], v[82:97]
	s_waitcnt lgkmcnt(0)
	v_mfma_f32_32x32x16_bf16 v[66:81], v[244:247], v[98:101], v[66:81]
	s_nop 9
	v_max_f32_e32 v235, v83, v83
	v_max_f32_e32 v236, v82, v82
	v_max_f32_e32 v235, v236, v235
	v_max3_f32 v235, v235, v84, v85
	v_max3_f32 v235, v235, v86, v87
	v_max3_f32 v235, v235, v88, v89
	v_max3_f32 v235, v235, v90, v91
	v_max3_f32 v235, v235, v92, v93
	v_max3_f32 v235, v235, v94, v95
	v_max3_f32 v235, v235, v96, v97
	v_max3_f32 v235, v235, v66, v67
	v_max3_f32 v235, v235, v68, v69
	v_max3_f32 v235, v235, v70, v71
	v_max3_f32 v235, v235, v72, v73
	v_max3_f32 v235, v235, v74, v75
	v_max3_f32 v235, v235, v76, v77
	v_max3_f32 v235, v235, v78, v79
	v_max3_f32 v235, v235, v80, v81
	v_mov_b32_e32 v236, v235
	s_nop 1
	v_permlane32_swap_b32_e32 v236, v235
	s_waitcnt lgkmcnt(0)
	v_max3_f32 v235, v218, v235, v236
	v_sub_f32_e32 v218, v218, v235
	v_exp_f32_e32 v218, v218
	s_nop 0
	v_cmp_neq_f32_e32 vcc, 1.0, v218
	s_cbranch_vccz .LBB0_1614
	v_mul_f32_e32 v64, v218, v64
	v_mul_f32_e32 v65, v218, v65
	v_mul_f32_e32 v62, v218, v62
	v_mul_f32_e32 v63, v218, v63
	v_mul_f32_e32 v60, v218, v60
	v_mul_f32_e32 v61, v218, v61
	v_mul_f32_e32 v58, v218, v58
	v_mul_f32_e32 v59, v218, v59
	v_mul_f32_e32 v56, v218, v56
	v_mul_f32_e32 v57, v218, v57
	v_mul_f32_e32 v54, v218, v54
	v_mul_f32_e32 v55, v218, v55
	v_mul_f32_e32 v52, v218, v52
	v_mul_f32_e32 v53, v218, v53
	v_mul_f32_e32 v50, v218, v50
	v_mul_f32_e32 v51, v218, v51
	v_mul_f32_e32 v48, v218, v48
	v_mul_f32_e32 v49, v218, v49
	v_mul_f32_e32 v46, v218, v46
	v_mul_f32_e32 v47, v218, v47
	v_mul_f32_e32 v44, v218, v44
	v_mul_f32_e32 v45, v218, v45
	v_mul_f32_e32 v42, v218, v42
	v_mul_f32_e32 v43, v218, v43
	v_mul_f32_e32 v40, v218, v40
	v_mul_f32_e32 v41, v218, v41
	v_mul_f32_e32 v38, v218, v38
	v_mul_f32_e32 v39, v218, v39
	v_mul_f32_e32 v36, v218, v36
	v_mul_f32_e32 v37, v218, v37
	v_mul_f32_e32 v34, v218, v34
	v_mul_f32_e32 v35, v218, v35
	v_mul_f32_e32 v32, v218, v32
	v_mul_f32_e32 v33, v218, v33
	v_mul_f32_e32 v30, v218, v30
	v_mul_f32_e32 v31, v218, v31
	v_mul_f32_e32 v28, v218, v28
	v_mul_f32_e32 v29, v218, v29
	v_mul_f32_e32 v26, v218, v26
	v_mul_f32_e32 v27, v218, v27
	v_mul_f32_e32 v24, v218, v24
	v_mul_f32_e32 v25, v218, v25
	v_mul_f32_e32 v22, v218, v22
	v_mul_f32_e32 v23, v218, v23
	v_mul_f32_e32 v20, v218, v20
	v_mul_f32_e32 v21, v218, v21
	v_mul_f32_e32 v18, v218, v18
	v_mul_f32_e32 v19, v218, v19
	v_mul_f32_e32 v16, v218, v16
	v_mul_f32_e32 v17, v218, v17
	v_mul_f32_e32 v14, v218, v14
	v_mul_f32_e32 v15, v218, v15
	v_mul_f32_e32 v12, v218, v12
	v_mul_f32_e32 v13, v218, v13
	v_mul_f32_e32 v10, v218, v10
	v_mul_f32_e32 v11, v218, v11
	v_mul_f32_e32 v8, v218, v8
	v_mul_f32_e32 v9, v218, v9
	v_mul_f32_e32 v6, v218, v6
	v_mul_f32_e32 v7, v218, v7
	v_mul_f32_e32 v4, v218, v4
	v_mul_f32_e32 v5, v218, v5
	v_mul_f32_e32 v2, v218, v2
	v_mul_f32_e32 v3, v218, v3

.LBB0_1618:
	s_andn2_b64 vcc, exec, s[48:49]
	s_barrier
	s_waitcnt vmcnt(4)
	ds_write_b128 v229, v[146:149]
	s_waitcnt vmcnt(3)
	ds_write_b128 v230, v[150:153]
	s_waitcnt vmcnt(2)
	ds_write_b128 v231, v[154:157]
	s_waitcnt vmcnt(1)
	ds_write_b128 v232, v[162:165] offset:25600
	s_waitcnt vmcnt(0)
	ds_write_b128 v233, v[158:161] offset:25600
	s_waitcnt lgkmcnt(0)
	s_barrier
	s_cbranch_vccnz .LBB0_1597
	v_add_u32_e32 v162, v226, v225
	ds_read_b128 v[66:69], v162
	ds_read_b128 v[146:149], v162 offset:32
	ds_read_b128 v[70:73], v162 offset:12800
	ds_read_b128 v[150:153], v162 offset:12832
	s_waitcnt lgkmcnt(3)
	v_mfma_f32_32x32x16_bf16 v[82:97], v[66:69], v[142:145], 0
	ds_read_b128 v[154:157], v162 offset:64
	ds_read_b128 v[158:161], v162 offset:12864
	s_waitcnt lgkmcnt(3)
	v_mfma_f32_32x32x16_bf16 v[66:81], v[70:73], v[142:145], 0
	v_mfma_f32_32x32x16_bf16 v[82:97], v[146:149], v[138:141], v[82:97]
	ds_read_b128 v[142:145], v162 offset:96
	ds_read_b128 v[146:149], v162 offset:12896
	s_waitcnt lgkmcnt(4)
	v_mfma_f32_32x32x16_bf16 v[66:81], v[150:153], v[138:141], v[66:81]
	s_waitcnt lgkmcnt(3)
	v_mfma_f32_32x32x16_bf16 v[82:97], v[154:157], v[134:137], v[82:97]
	ds_read_b128 v[138:141], v162 offset:128
	ds_read_b128 v[150:153], v162 offset:12928
	s_waitcnt lgkmcnt(4)
	v_mfma_f32_32x32x16_bf16 v[66:81], v[158:161], v[134:137], v[66:81]
	s_waitcnt lgkmcnt(3)
	v_mfma_f32_32x32x16_bf16 v[82:97], v[142:145], v[130:133], v[82:97]
	ds_read_b128 v[134:137], v162 offset:160
	ds_read_b128 v[142:145], v162 offset:12960
	s_waitcnt lgkmcnt(4)
	v_mfma_f32_32x32x16_bf16 v[66:81], v[146:149], v[130:133], v[66:81]
	s_waitcnt lgkmcnt(3)
	v_mfma_f32_32x32x16_bf16 v[82:97], v[138:141], v[126:129], v[82:97]
	ds_read_b128 v[130:133], v162 offset:192
	ds_read_b128 v[138:141], v162 offset:12992
	s_waitcnt lgkmcnt(4)
	v_mfma_f32_32x32x16_bf16 v[66:81], v[150:153], v[126:129], v[66:81]
	s_waitcnt lgkmcnt(3)
	v_mfma_f32_32x32x16_bf16 v[82:97], v[134:137], v[122:125], v[82:97]
	ds_read_b128 v[126:129], v162 offset:224
	ds_read_b128 v[134:137], v162 offset:13024
	s_waitcnt lgkmcnt(4)
	v_mfma_f32_32x32x16_bf16 v[66:81], v[142:145], v[122:125], v[66:81]
	s_waitcnt lgkmcnt(3)
	v_mfma_f32_32x32x16_bf16 v[82:97], v[130:133], v[118:121], v[82:97]
	ds_read_b128 v[122:125], v162 offset:256
	ds_read_b128 v[130:133], v162 offset:13056
	s_waitcnt lgkmcnt(4)
	v_mfma_f32_32x32x16_bf16 v[66:81], v[138:141], v[118:121], v[66:81]
	s_waitcnt lgkmcnt(3)
	v_mfma_f32_32x32x16_bf16 v[82:97], v[126:129], v[114:117], v[82:97]
	ds_read_b128 v[118:121], v162 offset:288
	ds_read_b128 v[126:129], v162 offset:13088
	s_waitcnt lgkmcnt(4)
	v_mfma_f32_32x32x16_bf16 v[66:81], v[134:137], v[114:117], v[66:81]
	s_waitcnt lgkmcnt(3)
	v_mfma_f32_32x32x16_bf16 v[82:97], v[122:125], v[110:113], v[82:97]
	ds_read_b128 v[114:117], v162 offset:320
	ds_read_b128 v[122:125], v162 offset:13120
	s_waitcnt lgkmcnt(4)
	v_mfma_f32_32x32x16_bf16 v[66:81], v[130:133], v[110:113], v[66:81]
	s_waitcnt lgkmcnt(3)
	v_mfma_f32_32x32x16_bf16 v[82:97], v[118:121], v[106:109], v[82:97]
	ds_read_b128 v[110:113], v162 offset:352
	ds_read_b128 v[118:121], v162 offset:13152
	s_waitcnt lgkmcnt(4)
	v_mfma_f32_32x32x16_bf16 v[66:81], v[126:129], v[106:109], v[66:81]
	s_waitcnt lgkmcnt(3)
	v_mfma_f32_32x32x16_bf16 v[82:97], v[114:117], v[102:105], v[82:97]
	s_waitcnt lgkmcnt(2)
	v_mfma_f32_32x32x16_bf16 v[66:81], v[122:125], v[102:105], v[66:81]
	s_waitcnt lgkmcnt(1)
	v_mfma_f32_32x32x16_bf16 v[82:97], v[110:113], v[98:101], v[82:97]
	s_waitcnt lgkmcnt(0)
	v_mfma_f32_32x32x16_bf16 v[66:81], v[118:121], v[98:101], v[66:81]
	s_nop 9
	v_max_f32_e32 v98, v83, v83
	v_max_f32_e32 v99, v82, v82
	v_max_f32_e32 v98, v99, v98
	v_max3_f32 v98, v98, v84, v85
	v_max3_f32 v98, v98, v86, v87
	v_max3_f32 v98, v98, v88, v89
	v_max3_f32 v98, v98, v90, v91
	v_max3_f32 v98, v98, v92, v93
	v_max3_f32 v98, v98, v94, v95
	v_max3_f32 v98, v98, v96, v97
	v_max3_f32 v98, v98, v66, v67
	v_max3_f32 v98, v98, v68, v69
	v_max3_f32 v98, v98, v70, v71
	v_max3_f32 v98, v98, v72, v73
	v_max3_f32 v98, v98, v74, v75
	v_max3_f32 v98, v98, v76, v77
	v_max3_f32 v98, v98, v78, v79
	v_max3_f32 v98, v98, v80, v81
	v_mov_b32_e32 v99, v98
	s_nop 1
	v_permlane32_swap_b32_e32 v99, v98
	s_waitcnt lgkmcnt(0)
	v_max3_f32 v99, v235, v98, v99
	v_sub_f32_e32 v98, v235, v99
	v_exp_f32_e32 v98, v98
	s_nop 0
	v_cmp_neq_f32_e32 vcc, 1.0, v98
	s_cbranch_vccz .LBB0_1596
	v_mul_f32_e32 v64, v98, v64
	v_mul_f32_e32 v65, v98, v65
	v_mul_f32_e32 v62, v98, v62
	v_mul_f32_e32 v63, v98, v63
	v_mul_f32_e32 v60, v98, v60
	v_mul_f32_e32 v61, v98, v61
	v_mul_f32_e32 v58, v98, v58
	v_mul_f32_e32 v59, v98, v59
	v_mul_f32_e32 v56, v98, v56
	v_mul_f32_e32 v57, v98, v57
	v_mul_f32_e32 v54, v98, v54
	v_mul_f32_e32 v55, v98, v55
	v_mul_f32_e32 v52, v98, v52
	v_mul_f32_e32 v53, v98, v53
	v_mul_f32_e32 v50, v98, v50
	v_mul_f32_e32 v51, v98, v51
	v_mul_f32_e32 v48, v98, v48
	v_mul_f32_e32 v49, v98, v49
	v_mul_f32_e32 v46, v98, v46
	v_mul_f32_e32 v47, v98, v47
	v_mul_f32_e32 v44, v98, v44
	v_mul_f32_e32 v45, v98, v45
	v_mul_f32_e32 v42, v98, v42
	v_mul_f32_e32 v43, v98, v43
	v_mul_f32_e32 v40, v98, v40
	v_mul_f32_e32 v41, v98, v41
	v_mul_f32_e32 v38, v98, v38
	v_mul_f32_e32 v39, v98, v39
	v_mul_f32_e32 v36, v98, v36
	v_mul_f32_e32 v37, v98, v37
	v_mul_f32_e32 v34, v98, v34
	v_mul_f32_e32 v35, v98, v35
	v_mul_f32_e32 v32, v98, v32
	v_mul_f32_e32 v33, v98, v33
	v_mul_f32_e32 v30, v98, v30
	v_mul_f32_e32 v31, v98, v31
	v_mul_f32_e32 v28, v98, v28
	v_mul_f32_e32 v29, v98, v29
	v_mul_f32_e32 v26, v98, v26
	v_mul_f32_e32 v27, v98, v27
	v_mul_f32_e32 v24, v98, v24
	v_mul_f32_e32 v25, v98, v25
	v_mul_f32_e32 v22, v98, v22
	v_mul_f32_e32 v23, v98, v23
	v_mul_f32_e32 v20, v98, v20
	v_mul_f32_e32 v21, v98, v21
	v_mul_f32_e32 v18, v98, v18
	v_mul_f32_e32 v19, v98, v19
	v_mul_f32_e32 v16, v98, v16
	v_mul_f32_e32 v17, v98, v17
	v_mul_f32_e32 v14, v98, v14
	v_mul_f32_e32 v15, v98, v15
	v_mul_f32_e32 v12, v98, v12
	v_mul_f32_e32 v13, v98, v13
	v_mul_f32_e32 v10, v98, v10
	v_mul_f32_e32 v11, v98, v11
	v_mul_f32_e32 v8, v98, v8
	v_mul_f32_e32 v9, v98, v9
	v_mul_f32_e32 v6, v98, v6
	v_mul_f32_e32 v7, v98, v7
	v_mul_f32_e32 v4, v98, v4
	v_mul_f32_e32 v5, v98, v5
	v_mul_f32_e32 v2, v98, v2
	v_mul_f32_e32 v3, v98, v3
	s_branch .LBB0_1596
